# job3 loop pad trimming: the eight V fragment reads fill the MFMA-to-VALU hazard pad after the QK chain (s_nop 11 -> reads + s_nop 3), duplicates removed from both softmax paths
# baseline (speedup 1.0000x reference)
.Lj3ld_norka:
	s_or_b64 exec, exec, s[6:7]
	s_waitcnt lgkmcnt(0)
	v_mfma_f32_32x32x16_bf16 v[130:145], v[232:235], v[236:239], v[130:145]
	ds_read_b64_tr_b16 v[232:233], v222
	ds_read_b64_tr_b16 v[234:235], v222 offset:4736
	ds_read_b64_tr_b16 v[236:237], v222 offset:64
	ds_read_b64_tr_b16 v[238:239], v222 offset:4800
	ds_read_b64_tr_b16 v[240:241], v222 offset:128
	ds_read_b64_tr_b16 v[242:243], v222 offset:4864
	ds_read_b64_tr_b16 v[246:247], v222 offset:192
	ds_read_b64_tr_b16 v[248:249], v222 offset:4928
	s_nop 3
	v_mov_b32_e32 v146, v130
	v_mov_b32_e32 v147, v131
	v_max3_f32 v130, v146, v147, v132
	v_max3_f32 v131, v139, v140, v141
	v_max3_f32 v130, v130, v133, v134
	v_max3_f32 v131, v131, v142, v143
	v_max3_f32 v130, v130, v135, v136
	v_max3_f32 v131, v131, v144, v145
	v_max3_f32 v130, v130, v137, v138
	v_max_f32_e32 v130, v130, v131
	v_sub_f32_e32 v131, v230, v130
	v_cmp_gt_f32_e32 vcc, 0xc2800000, v131
	s_cbranch_vccnz .Llazy0_full
	v_mov_b32_e32 v229, v230
	v_mov_b32_e32 v130, 1.0
	s_branch .LBB0_946
.Llazy0_full:
	v_mbcnt_hi_u32_b32 v131, -1, v217
	v_and_b32_e32 v149, 64, v131
	v_xor_b32_e32 v148, 32, v131
	v_add_u32_e32 v149, 64, v149
	v_cmp_lt_i32_e32 vcc, v148, v149
	s_nop 1
	v_cndmask_b32_e32 v131, v131, v148, vcc
	v_lshlrev_b32_e32 v131, 2, v131
	ds_bpermute_b32 v131, v131, v130
	s_waitcnt lgkmcnt(0)
	v_max3_f32 v229, v230, v130, v131
	v_sub_f32_e32 v130, v230, v229
	v_exp_f32_e32 v130, v130
	s_nop 0
	v_cmp_neq_f32_e32 vcc, 1.0, v130
	s_cbranch_vccz .LBB0_946
	v_pk_mul_f32 v[128:129], v[128:129], v[130:131] op_sel_hi:[1,0]
	v_pk_mul_f32 v[126:127], v[126:127], v[130:131] op_sel_hi:[1,0]
	v_pk_mul_f32 v[124:125], v[124:125], v[130:131] op_sel_hi:[1,0]
	v_pk_mul_f32 v[122:123], v[122:123], v[130:131] op_sel_hi:[1,0]
	v_pk_mul_f32 v[120:121], v[120:121], v[130:131] op_sel_hi:[1,0]
	v_pk_mul_f32 v[118:119], v[118:119], v[130:131] op_sel_hi:[1,0]
	v_pk_mul_f32 v[116:117], v[116:117], v[130:131] op_sel_hi:[1,0]
	v_pk_mul_f32 v[114:115], v[114:115], v[130:131] op_sel_hi:[1,0]
	v_pk_mul_f32 v[112:113], v[112:113], v[130:131] op_sel_hi:[1,0]
	v_pk_mul_f32 v[110:111], v[110:111], v[130:131] op_sel_hi:[1,0]
	v_pk_mul_f32 v[108:109], v[108:109], v[130:131] op_sel_hi:[1,0]
	v_pk_mul_f32 v[106:107], v[106:107], v[130:131] op_sel_hi:[1,0]
	v_pk_mul_f32 v[104:105], v[104:105], v[130:131] op_sel_hi:[1,0]
	v_pk_mul_f32 v[102:103], v[102:103], v[130:131] op_sel_hi:[1,0]
	v_pk_mul_f32 v[100:101], v[100:101], v[130:131] op_sel_hi:[1,0]
	v_pk_mul_f32 v[98:99], v[98:99], v[130:131] op_sel_hi:[1,0]
	v_pk_mul_f32 v[96:97], v[96:97], v[130:131] op_sel_hi:[1,0]
	v_pk_mul_f32 v[94:95], v[94:95], v[130:131] op_sel_hi:[1,0]
	v_pk_mul_f32 v[92:93], v[92:93], v[130:131] op_sel_hi:[1,0]
	v_pk_mul_f32 v[90:91], v[90:91], v[130:131] op_sel_hi:[1,0]
	v_pk_mul_f32 v[88:89], v[88:89], v[130:131] op_sel_hi:[1,0]
	v_pk_mul_f32 v[86:87], v[86:87], v[130:131] op_sel_hi:[1,0]
	v_pk_mul_f32 v[84:85], v[84:85], v[130:131] op_sel_hi:[1,0]
	v_pk_mul_f32 v[82:83], v[82:83], v[130:131] op_sel_hi:[1,0]
	v_pk_mul_f32 v[80:81], v[80:81], v[130:131] op_sel_hi:[1,0]
	v_pk_mul_f32 v[78:79], v[78:79], v[130:131] op_sel_hi:[1,0]
	v_pk_mul_f32 v[76:77], v[76:77], v[130:131] op_sel_hi:[1,0]
	v_pk_mul_f32 v[74:75], v[74:75], v[130:131] op_sel_hi:[1,0]
	v_pk_mul_f32 v[72:73], v[72:73], v[130:131] op_sel_hi:[1,0]
	v_pk_mul_f32 v[70:71], v[70:71], v[130:131] op_sel_hi:[1,0]
	v_pk_mul_f32 v[68:69], v[68:69], v[130:131] op_sel_hi:[1,0]
	v_pk_mul_f32 v[66:67], v[66:67], v[130:131] op_sel_hi:[1,0]
	v_pk_mul_f32 v[64:65], v[64:65], v[130:131] op_sel_hi:[1,0]
	v_pk_mul_f32 v[62:63], v[62:63], v[130:131] op_sel_hi:[1,0]
	v_pk_mul_f32 v[60:61], v[60:61], v[130:131] op_sel_hi:[1,0]
	v_pk_mul_f32 v[58:59], v[58:59], v[130:131] op_sel_hi:[1,0]
	v_pk_mul_f32 v[56:57], v[56:57], v[130:131] op_sel_hi:[1,0]
	v_pk_mul_f32 v[54:55], v[54:55], v[130:131] op_sel_hi:[1,0]
	v_pk_mul_f32 v[52:53], v[52:53], v[130:131] op_sel_hi:[1,0]
	v_pk_mul_f32 v[50:51], v[50:51], v[130:131] op_sel_hi:[1,0]
	v_pk_mul_f32 v[48:49], v[48:49], v[130:131] op_sel_hi:[1,0]
	v_pk_mul_f32 v[46:47], v[46:47], v[130:131] op_sel_hi:[1,0]
	v_pk_mul_f32 v[44:45], v[44:45], v[130:131] op_sel_hi:[1,0]
	v_pk_mul_f32 v[42:43], v[42:43], v[130:131] op_sel_hi:[1,0]
	v_pk_mul_f32 v[40:41], v[40:41], v[130:131] op_sel_hi:[1,0]
	v_pk_mul_f32 v[38:39], v[38:39], v[130:131] op_sel_hi:[1,0]
	v_pk_mul_f32 v[36:37], v[36:37], v[130:131] op_sel_hi:[1,0]
	v_pk_mul_f32 v[34:35], v[34:35], v[130:131] op_sel_hi:[1,0]
	v_pk_mul_f32 v[32:33], v[32:33], v[130:131] op_sel_hi:[1,0]
	v_pk_mul_f32 v[30:31], v[30:31], v[130:131] op_sel_hi:[1,0]
	v_pk_mul_f32 v[28:29], v[28:29], v[130:131] op_sel_hi:[1,0]
	v_pk_mul_f32 v[26:27], v[26:27], v[130:131] op_sel_hi:[1,0]
	v_pk_mul_f32 v[24:25], v[24:25], v[130:131] op_sel_hi:[1,0]
	v_pk_mul_f32 v[22:23], v[22:23], v[130:131] op_sel_hi:[1,0]
	v_pk_mul_f32 v[20:21], v[20:21], v[130:131] op_sel_hi:[1,0]
	v_pk_mul_f32 v[18:19], v[18:19], v[130:131] op_sel_hi:[1,0]
	v_pk_mul_f32 v[16:17], v[16:17], v[130:131] op_sel_hi:[1,0]
	v_pk_mul_f32 v[14:15], v[14:15], v[130:131] op_sel_hi:[1,0]
	v_pk_mul_f32 v[12:13], v[12:13], v[130:131] op_sel_hi:[1,0]
	v_pk_mul_f32 v[10:11], v[10:11], v[130:131] op_sel_hi:[1,0]
	v_pk_mul_f32 v[8:9], v[8:9], v[130:131] op_sel_hi:[1,0]
	v_pk_mul_f32 v[6:7], v[6:7], v[130:131] op_sel_hi:[1,0]
	v_pk_mul_f32 v[4:5], v[4:5], v[130:131] op_sel_hi:[1,0]
	v_pk_mul_f32 v[2:3], v[2:3], v[130:131] op_sel_hi:[1,0]
